# grid barrier top level: XCD leaders poll the TOP arrival counter (>= target) instead of a separate TOPGEN word; TOPGEN add dropped
# speedup vs baseline: 1.0063x; 1.0063x over previous
.LBB0_255:
	s_or_b64 exec, exec, s[16:17]
	v_cvt_f32_u32_e32 v3, v0
	s_waitcnt vmcnt(0)
	v_readfirstlane_b32 s3, v2
	s_add_u32 s16, s10, 0x3400
	s_addc_u32 s17, s11, 0
	v_rcp_iflag_f32_e32 v3, v3
	v_add_u32_e32 v1, s3, v1
	v_add_u32_e32 v4, 1, v1
	s_mov_b64 s[18:19], 0
	v_mul_f32_e32 v2, 0x4f7ffffe, v3
	v_cvt_u32_f32_e32 v2, v2
	v_sub_u32_e32 v3, 0, v0
	v_mul_lo_u32 v3, v3, v2
	v_mul_hi_u32 v3, v2, v3
	v_add_u32_e32 v2, v2, v3
	v_mul_hi_u32 v2, v1, v2
	v_mul_lo_u32 v3, v2, v0
	v_sub_u32_e32 v1, v1, v3
	v_add_u32_e32 v5, 1, v2
	v_cmp_ge_u32_e32 vcc, v1, v0
	v_sub_u32_e32 v3, v1, v0
	s_nop 0
	v_cndmask_b32_e32 v2, v2, v5, vcc
	v_cndmask_b32_e32 v1, v1, v3, vcc
	v_add_u32_e32 v3, 1, v2
	v_cmp_ge_u32_e32 vcc, v1, v0
	s_nop 1
	v_cndmask_b32_e32 v2, v2, v3, vcc
	v_mul_lo_u32 v1, v0, v2
	v_add_u32_e32 v5, v1, v0
	v_cmp_ne_u32_e32 vcc, v4, v5
	v_mov_b64_e32 v[0:1], s[16:17]
	s_and_saveexec_b64 s[14:15], vcc
	s_cbranch_execz .LBB0_267
	v_mov_b32_e32 v0, 0
	global_load_dword v1, v0, s[16:17] sc1
	s_mov_b64 s[22:23], 0
	s_waitcnt vmcnt(0)
	v_cmp_lt_u32_e32 vcc, v1, v5
	s_and_saveexec_b64 s[20:21], vcc
	s_cbranch_execz .LBB0_266
	s_add_u32 s18, s10, 0x200
	s_addc_u32 s19, s11, 0
	s_mov_b32 s3, 1
	s_mov_b64 s[10:11], 0
	s_branch .LBB0_259

.LBB0_263:
	global_load_dword v1, v0, s[16:17] sc1
	s_add_i32 s3, s3, 1
	s_mov_b64 s[24:25], -1
	s_waitcnt vmcnt(0)
	v_cmp_ge_u32_e32 vcc, v1, v5
	s_orn2_b64 s[28:29], vcc, exec
	s_branch .LBB0_258

.LBB0_531:
	s_or_b64 exec, exec, s[12:13]
	v_cvt_f32_u32_e32 v3, v0
	s_waitcnt vmcnt(0)
	v_readfirstlane_b32 s3, v2
	s_add_u32 s12, s6, 0x3400
	s_addc_u32 s13, s7, 0
	v_rcp_iflag_f32_e32 v3, v3
	v_add_u32_e32 v1, s3, v1
	v_add_u32_e32 v4, 1, v1
	s_mov_b64 s[14:15], 0
	v_mul_f32_e32 v2, 0x4f7ffffe, v3
	v_cvt_u32_f32_e32 v2, v2
	v_sub_u32_e32 v3, 0, v0
	v_mul_lo_u32 v3, v3, v2
	v_mul_hi_u32 v3, v2, v3
	v_add_u32_e32 v2, v2, v3
	v_mul_hi_u32 v2, v1, v2
	v_mul_lo_u32 v3, v2, v0
	v_sub_u32_e32 v1, v1, v3
	v_add_u32_e32 v5, 1, v2
	v_cmp_ge_u32_e32 vcc, v1, v0
	v_sub_u32_e32 v3, v1, v0
	s_nop 0
	v_cndmask_b32_e32 v2, v2, v5, vcc
	v_cndmask_b32_e32 v1, v1, v3, vcc
	v_add_u32_e32 v3, 1, v2
	v_cmp_ge_u32_e32 vcc, v1, v0
	s_nop 1
	v_cndmask_b32_e32 v2, v2, v3, vcc
	v_mul_lo_u32 v1, v0, v2
	v_add_u32_e32 v5, v1, v0
	v_cmp_ne_u32_e32 vcc, v4, v5
	v_mov_b64_e32 v[0:1], s[12:13]
	s_and_saveexec_b64 s[10:11], vcc
	s_cbranch_execz .LBB0_543
	v_mov_b32_e32 v0, 0
	global_load_dword v1, v0, s[12:13] sc1
	s_mov_b64 s[18:19], 0
	s_waitcnt vmcnt(0)
	v_cmp_lt_u32_e32 vcc, v1, v5
	s_and_saveexec_b64 s[16:17], vcc
	s_cbranch_execz .LBB0_542
	s_add_u32 s14, s6, 0x200
	s_addc_u32 s15, s7, 0
	s_mov_b32 s3, 1
	s_mov_b64 s[6:7], 0
	s_branch .LBB0_535

.LBB0_539:
	global_load_dword v1, v0, s[12:13] sc1
	s_add_i32 s3, s3, 1
	s_mov_b64 s[20:21], -1
	s_waitcnt vmcnt(0)
	v_cmp_ge_u32_e32 vcc, v1, v5
	s_orn2_b64 s[24:25], vcc, exec
	s_branch .LBB0_534
